# ret_prep: batch the 8 V-staging loads and hoist the 12 loads of each rope-loop trip (on top of v5)
# speedup vs baseline: 1.0105x; 1.0105x over previous
; DI void phase_ret_prep(PrmC p, int ri, unsigned char* smem) {
;     ...
;         for (int i = 0; i < 8; ++i) { const int idx = tid + i * NTHR, pos = idx >> 6, seg = idx & 63;
;             *(uint4*)(vt_l + pos * 520 + seg * 8) = *(const uint4*)(P1 + (size_t)(row0 + pos) * 2048 + hp * 512 + seg * 8); }
;         if (tid < 256) { const int j = tid & 63, hh2 = (tid >> 6) & 1, dir2 = tid >> 7; const float dl = p->ret_decay_logit[(size_t)ri * 16 + dir2 * 8 + 2 * hp + hh2];
;             dec_l[tid] = exp2f(-log1pf(__expf(-dl)) * 1.4426950408889634f * (float)(dir2 ? j : 63 - j)); }
.LBB0_674:
	s_ashr_i32 s14, s5, 2
	s_lshl_b32 s15, s14, 6
	s_and_b32 s18, s5, 3
	v_add_u32_e32 v2, s15, v70
	s_lshl_b32 s10, s18, 10
	s_mov_b32 s11, s36
	v_ashrrev_i32_e32 v3, 31, v2
	v_lshl_add_u64 v[6:7], v[10:11], 0, s[10:11]
	v_lshlrev_b64 v[2:3], 12, v[2:3]
	v_lshl_add_u64 v[2:3], v[6:7], 0, v[2:3]
	s_waitcnt vmcnt(63) expcnt(7) lgkmcnt(15)
	s_barrier
	v_add_u32_e32 v140, s15, v70
	v_ashrrev_i32_e32 v141, 31, v140
	v_lshlrev_b64 v[140:141], 12, v[140:141]
	v_lshl_add_u64 v[140:141], v[6:7], 0, v[140:141]
	global_load_dwordx4 v[108:111], v[140:141], off
	v_add_u32_e32 v142, s15, v77
	v_ashrrev_i32_e32 v143, 31, v142
	v_lshlrev_b64 v[142:143], 12, v[142:143]
	v_lshl_add_u64 v[142:143], v[6:7], 0, v[142:143]
	global_load_dwordx4 v[112:115], v[142:143], off
	v_add_u32_e32 v144, s15, v79
	v_ashrrev_i32_e32 v145, 31, v144
	v_lshlrev_b64 v[144:145], 12, v[144:145]
	v_lshl_add_u64 v[144:145], v[6:7], 0, v[144:145]
	global_load_dwordx4 v[116:119], v[144:145], off
	v_add_u32_e32 v146, s15, v81
	v_ashrrev_i32_e32 v147, 31, v146
	v_lshlrev_b64 v[146:147], 12, v[146:147]
	v_lshl_add_u64 v[146:147], v[6:7], 0, v[146:147]
	global_load_dwordx4 v[120:123], v[146:147], off
	v_add_u32_e32 v148, s15, v83
	v_ashrrev_i32_e32 v149, 31, v148
	v_lshlrev_b64 v[148:149], 12, v[148:149]
	v_lshl_add_u64 v[148:149], v[6:7], 0, v[148:149]
	global_load_dwordx4 v[124:127], v[148:149], off
	v_add_u32_e32 v150, s15, v85
	v_ashrrev_i32_e32 v151, 31, v150
	v_lshlrev_b64 v[150:151], 12, v[150:151]
	v_lshl_add_u64 v[150:151], v[6:7], 0, v[150:151]
	global_load_dwordx4 v[128:131], v[150:151], off
	v_add_u32_e32 v152, s15, v87
	v_ashrrev_i32_e32 v153, 31, v152
	v_lshlrev_b64 v[152:153], 12, v[152:153]
	v_lshl_add_u64 v[152:153], v[6:7], 0, v[152:153]
	global_load_dwordx4 v[132:135], v[152:153], off
	v_add_u32_e32 v154, s15, v89
	v_ashrrev_i32_e32 v155, 31, v154
	v_lshlrev_b64 v[154:155], 12, v[154:155]
	v_lshl_add_u64 v[154:155], v[6:7], 0, v[154:155]
	global_load_dwordx4 v[136:139], v[154:155], off
	s_waitcnt vmcnt(0)
	ds_write_b128 v76, v[108:111]
	ds_write_b128 v78, v[112:115]
	ds_write_b128 v80, v[116:119]
	ds_write_b128 v82, v[120:123]
	ds_write_b128 v84, v[124:127]
	ds_write_b128 v86, v[128:131]
	ds_write_b128 v88, v[132:135]
	ds_write_b128 v90, v[136:139]
	s_and_saveexec_b64 s[10:11], s[6:7]
	s_cbranch_execz .LBB0_676
	s_load_dwordx2 s[16:17], s[0:1], 0x98
	v_readlane_b32 s4, v254, 22
	v_mov_b32_e32 v29, v1
	s_waitcnt lgkmcnt(0)
	s_add_u32 s16, s16, s4
	s_addc_u32 s17, s17, 0
	v_lshl_add_u64 v[2:3], v[12:13], 2, s[16:17]
	s_lshl_b32 s16, s18, 3
	s_mov_b32 s17, s36
	v_lshl_add_u64 v[2:3], v[2:3], 0, s[16:17]
	v_lshl_add_u64 v[2:3], v[2:3], 0, v[28:29]
	global_load_dword v0, v[2:3], off
	s_mov_b32 s4, 0x3f2aaaab
	s_waitcnt vmcnt(0)
	v_mul_f32_e32 v0, 0xbfb8aa3b, v0
	v_exp_f32_e32 v0, v0
	s_nop 0
	v_add_f32_e32 v4, 1.0, v0
	v_add_f32_e32 v2, -1.0, v4
	v_sub_f32_e32 v3, v2, v4
	v_add_f32_e32 v3, 1.0, v3
	v_sub_f32_e32 v2, v0, v2
	v_add_f32_e32 v5, v2, v3
	v_frexp_mant_f32_e32 v2, v4
	v_cmp_gt_f32_e32 vcc, s4, v2
	v_cvt_f64_f32_e32 v[2:3], v4
	v_frexp_exp_i32_f64_e32 v2, v[2:3]
	v_subbrev_co_u32_e32 v29, vcc, 0, v2, vcc
	v_sub_u32_e32 v2, 0, v29
	v_ldexp_f32 v3, v4, v2
	v_add_f32_e32 v4, -1.0, v3
	v_add_f32_e32 v6, 1.0, v3
	v_ldexp_f32 v2, v5, v2
	v_add_f32_e32 v5, 1.0, v4
	v_add_f32_e32 v7, -1.0, v6
	v_sub_f32_e32 v5, v3, v5
	v_sub_f32_e32 v3, v3, v7
	v_add_f32_e32 v5, v2, v5
	v_add_f32_e32 v2, v2, v3
	v_add_f32_e32 v30, v6, v2
	v_rcp_f32_e32 v32, v30
	v_sub_f32_e32 v3, v30, v6
	v_sub_f32_e32 v31, v2, v3
	v_add_f32_e32 v3, v4, v5
	v_mul_f32_e32 v34, v3, v32
	v_sub_f32_e32 v2, v3, v4
	v_mul_f32_e32 v4, v30, v34
	v_fma_f32 v6, v34, v30, -v4
	v_fmac_f32_e32 v6, v34, v31
	v_sub_f32_e32 v33, v5, v2
	v_add_f32_e32 v2, v4, v6
	v_sub_f32_e32 v5, v3, v2
	v_pk_add_f32 v[8:9], v[2:3], v[4:5] neg_lo:[0,1] neg_hi:[0,1]
	v_mov_b32_e32 v7, v2
	v_pk_add_f32 v[2:3], v[8:9], v[6:7] neg_lo:[0,1] neg_hi:[0,1]
	s_mov_b32 s4, 0x3f317218
	v_add_f32_e32 v3, v33, v3
	v_add_f32_e32 v2, v2, v3
	v_add_f32_e32 v3, v5, v2
	v_mul_f32_e32 v33, v32, v3
	v_mul_f32_e32 v4, v30, v33
	v_fma_f32 v6, v33, v30, -v4
	v_fmac_f32_e32 v6, v33, v31
	v_sub_f32_e32 v5, v5, v3
	v_add_f32_e32 v30, v2, v5
	v_add_f32_e32 v2, v4, v6
	v_sub_f32_e32 v5, v3, v2
	v_pk_add_f32 v[8:9], v[2:3], v[4:5] neg_lo:[0,1] neg_hi:[0,1]
	v_mov_b32_e32 v7, v2
	v_pk_add_f32 v[2:3], v[8:9], v[6:7] neg_lo:[0,1] neg_hi:[0,1]
	s_nop 0
	v_add_f32_e32 v3, v30, v3
	v_add_f32_e32 v2, v2, v3
	v_add_f32_e32 v3, v34, v33
	v_add_f32_e32 v2, v5, v2
	v_sub_f32_e32 v4, v3, v34
	v_mul_f32_e32 v2, v32, v2
	v_sub_f32_e32 v4, v33, v4
	v_add_f32_e32 v4, v4, v2
	v_add_f32_e32 v6, v3, v4
	v_mul_f32_e32 v7, v6, v6
	v_fmamk_f32 v2, v7, 0x3e9b6dac, v239
	v_fmaak_f32 v197, v7, v2, 0x3f2aaada
	v_cvt_f32_i32_e32 v2, v29
	v_sub_f32_e32 v3, v6, v3
	v_sub_f32_e32 v3, v4, v3
	v_ldexp_f32 v8, v3, 1
	v_mul_f32_e32 v3, v6, v7
	v_ldexp_f32 v5, v6, 1
	v_pk_mul_f32 v[6:7], v[2:3], v[196:197]
	s_nop 0
	v_fma_f32 v4, v2, s4, -v6
	v_fmac_f32_e32 v4, 0xb102e308, v2
	v_pk_add_f32 v[2:3], v[6:7], v[4:5]
	s_mov_b32 s4, 0x7f800000
	v_sub_f32_e32 v5, v3, v5
	v_sub_f32_e32 v5, v7, v5
	v_add_f32_e32 v9, v8, v5
	v_mov_b32_e32 v8, v6
	v_pk_add_f32 v[6:7], v[2:3], v[6:7] neg_lo:[0,1] neg_hi:[0,1]
	v_pk_add_f32 v[30:31], v[2:3], v[8:9]
	v_mov_b32_e32 v5, v2
	v_mov_b32_e32 v7, v31
	v_pk_add_f32 v[32:33], v[4:5], v[6:7] neg_lo:[0,1] neg_hi:[0,1]
	v_pk_add_f32 v[4:5], v[4:5], v[6:7]
	v_mov_b32_e32 v8, v9
	v_pk_add_f32 v[6:7], v[4:5], v[2:3] op_sel:[1,0] op_sel_hi:[0,1] neg_lo:[0,1] neg_hi:[0,1]
	v_pk_add_f32 v[34:35], v[30:31], v[6:7] op_sel_hi:[1,0] neg_lo:[0,1] neg_hi:[0,1]
	v_mov_b32_e32 v30, v31
	v_mov_b32_e32 v31, v5
	v_pk_mov_b32 v[6:7], v[2:3], v[6:7] op_sel:[1,0]
	v_mov_b32_e32 v9, v2
	v_pk_add_f32 v[6:7], v[30:31], v[6:7] neg_lo:[0,1] neg_hi:[0,1]
	v_mov_b32_e32 v34, v32
	v_pk_add_f32 v[2:3], v[8:9], v[6:7] neg_lo:[0,1] neg_hi:[0,1]
	v_mov_b32_e32 v33, v5
	v_pk_add_f32 v[6:7], v[34:35], v[2:3]
	v_cmp_neq_f32_e32 vcc, s4, v0
	v_pk_add_f32 v[8:9], v[6:7], v[6:7] op_sel:[0,1] op_sel_hi:[1,0]
	s_mov_b32 s4, 0x33800000
	v_pk_add_f32 v[4:5], v[4:5], v[8:9] op_sel:[1,0] op_sel_hi:[0,1]
	v_mov_b32_e32 v7, v4
	v_pk_add_f32 v[30:31], v[6:7], v[32:33] neg_lo:[0,1] neg_hi:[0,1]
	v_mov_b32_e32 v3, v8
	v_sub_f32_e32 v5, v6, v30
	v_pk_add_f32 v[2:3], v[2:3], v[30:31] neg_lo:[0,1] neg_hi:[0,1]
	v_sub_f32_e32 v5, v32, v5
	v_add_f32_e32 v2, v2, v5
	v_add_f32_e32 v2, v2, v3
	v_add_f32_e32 v2, v4, v2
	v_cndmask_b32_e32 v2, v243, v2, vcc
	v_cmp_ngt_f32_e32 vcc, -1.0, v0
	s_nop 1
	v_cndmask_b32_e32 v2, v253, v2, vcc
	v_cmp_neq_f32_e32 vcc, -1.0, v0
	s_nop 1
	v_cndmask_b32_e32 v2, v241, v2, vcc
	v_cmp_lt_f32_e64 vcc, |v0|, s4
	s_nop 1
	v_cndmask_b32_e32 v0, v2, v0, vcc
	v_mul_f32_e32 v0, 0xbfb8aa3b, v0
	v_mul_f32_e32 v2, v0, v71
	v_cmp_gt_f32_e32 vcc, s72, v2
	s_nop 1
	v_cndmask_b32_e32 v2, 0, v248, vcc
	v_fmac_f32_e32 v2, v0, v71
	v_exp_f32_e32 v0, v2
	v_cndmask_b32_e32 v2, 0, v249, vcc
	v_ldexp_f32 v0, v0, v2
	ds_write_b32 v72, v0

; DI void phase_ret_prep(PrmC p, int ri, unsigned char* smem) {
;     ...
;           for (int tp = 0; tp < 4; ++tp) {
;               const int pos = 8 * wave + 2 * tp + (lane >> 5), row = row0 + pos;
;               float q[8], k[8]; unpack8(*(const uint4*)(P0 + (size_t)row * 2048 + hp * 256 + c), q); unpack8(*(const uint4*)(P0 + (size_t)row * 2048 + 1024 + hp * 256 + c), k);
;               if (lat) {
;                   const float2* rt = RT + (size_t)(row & 2047) * 64 + (wo & 63);
; #pragma unroll
;                   for (int e = 0; e < 8; ++e) { const float2 cs = rt[e]; const float qp = __shfl_xor(q[e], 8), kp = __shfl_xor(k[e], 8);
;                       q[e] = q[e] * cs.x + (firsth ? -qp : qp) * cs.y; k[e] = k[e] * cs.x + (firsth ? -kp : kp) * cs.y; }
;               }
.LBB0_678:
	v_ashrrev_i32_e32 v37, 31, v36
	v_lshlrev_b64 v[156:157], 12, v[36:37]
	v_lshl_add_u64 v[156:157], v[34:35], 0, v[156:157]
	global_load_dwordx4 v[108:111], v[156:157], off
	global_load_dwordx4 v[112:115], v[156:157], off offset:2048
	v_add_u32_e32 v158, 2, v36
	v_ashrrev_i32_e32 v159, 31, v158
	v_lshlrev_b64 v[158:159], 12, v[158:159]
	v_lshl_add_u64 v[158:159], v[34:35], 0, v[158:159]
	global_load_dwordx4 v[116:119], v[158:159], off
	global_load_dwordx4 v[120:123], v[158:159], off offset:2048
	v_add_u32_e32 v160, s15, v29
	v_add_u32_e32 v162, 0x80, v160
	v_and_b32_e32 v160, 0x1ffc0, v160
	v_lshlrev_b32_e32 v160, 3, v160
	v_mov_b32_e32 v161, 0
	v_lshl_add_u64 v[160:161], v[18:19], 0, v[160:161]
	global_load_dwordx4 v[124:127], v[160:161], off offset:32
	global_load_dwordx4 v[128:131], v[160:161], off offset:16
	global_load_dwordx4 v[132:135], v[160:161], off
	global_load_dwordx4 v[136:139], v[160:161], off offset:48
	v_and_b32_e32 v162, 0x1ffc0, v162
	v_lshlrev_b32_e32 v162, 3, v162
	v_mov_b32_e32 v163, 0
	v_lshl_add_u64 v[162:163], v[18:19], 0, v[162:163]
	global_load_dwordx4 v[140:143], v[162:163], off offset:32
	global_load_dwordx4 v[144:147], v[162:163], off offset:16
	global_load_dwordx4 v[148:151], v[162:163], off
	global_load_dwordx4 v[152:155], v[162:163], off offset:48
	s_waitcnt vmcnt(0)
	v_lshlrev_b64 v[2:3], 12, v[36:37]
	v_lshl_add_u64 v[6:7], v[34:35], 0, v[2:3]
	v_mov_b64_e32 v[2:3], v[108:109]
	v_mov_b64_e32 v[4:5], v[110:111]
	s_nop 0
	v_mov_b64_e32 v[6:7], v[112:113]
	v_mov_b64_e32 v[8:9], v[114:115]
	v_cndmask_b32_e64 v0, 0, 1, s[16:17]
	v_cmp_ne_u32_e64 s[10:11], 1, v0
	s_andn2_b64 vcc, exec, s[16:17]
	v_add_u32_e32 v97, s15, v29
	v_lshlrev_b32_e32 v42, 16, v2
	v_and_b32_e32 v43, 0xffff0000, v2
	v_lshlrev_b32_e32 v46, 16, v3
	v_and_b32_e32 v47, 0xffff0000, v3
	v_lshlrev_b32_e32 v38, 16, v4
	v_and_b32_e32 v39, 0xffff0000, v4
	v_lshlrev_b32_e32 v40, 16, v5
	v_and_b32_e32 v41, 0xffff0000, v5
	v_lshlrev_b32_e32 v66, 16, v6
	v_and_b32_e32 v44, 0xffff0000, v6
	v_lshlrev_b32_e32 v67, 16, v7
	v_and_b32_e32 v45, 0xffff0000, v7
	v_lshlrev_b32_e32 v62, 16, v8
	v_and_b32_e32 v58, 0xffff0000, v8
	v_lshlrev_b32_e32 v63, 16, v9
	v_and_b32_e32 v59, 0xffff0000, v9
	s_cbranch_vccnz .LBB0_680
	v_and_b32_e32 v0, 0x1ffc0, v97
	v_lshlrev_b32_e32 v0, 3, v0
	v_and_b32_e32 v4, 64, v240
	v_lshl_add_u64 v[2:3], v[18:19], 0, v[0:1]
	v_xor_b32_e32 v0, 8, v240
	v_add_u32_e32 v4, 64, v4
	v_cmp_lt_i32_e32 vcc, v0, v4
	v_mov_b64_e32 v[6:7], v[124:125]
	v_mov_b64_e32 v[8:9], v[126:127]
	v_mov_b64_e32 v[98:99], v[128:129]
	v_mov_b64_e32 v[100:101], v[130:131]
	v_mov_b64_e32 v[102:103], v[132:133]
	v_mov_b64_e32 v[104:105], v[134:135]
	s_nop 0
	v_mov_b64_e32 v[2:3], v[136:137]
	v_mov_b64_e32 v[4:5], v[138:139]
	v_cndmask_b32_e32 v0, v240, v0, vcc
	v_lshlrev_b32_e32 v0, 2, v0
	v_mov_b32_e32 v64, v42
	v_mov_b32_e32 v61, v43
	v_mov_b32_e32 v55, v44
	v_mov_b32_e32 v68, v46
	v_mov_b32_e32 v56, v66
	v_mov_b32_e32 v52, v7
	v_mov_b32_e32 v53, v8
	ds_bpermute_b32 v7, v0, v42
	ds_bpermute_b32 v8, v0, v66
	v_mov_b32_e32 v48, v103
	v_mov_b32_e32 v103, v105
	v_mov_b32_e32 v49, v104
	s_waitcnt lgkmcnt(1)
	v_cndmask_b32_e64 v60, v7, -v7, s[8:9]
	s_waitcnt lgkmcnt(0)
	v_cndmask_b32_e64 v54, v8, -v8, s[8:9]
	ds_bpermute_b32 v7, v0, v43
	ds_bpermute_b32 v8, v0, v44
	v_mov_b32_e32 v50, v99
	v_mov_b32_e32 v99, v101
	v_mov_b32_e32 v51, v100
	s_waitcnt lgkmcnt(1)
	v_cndmask_b32_e64 v65, v7, -v7, s[8:9]
	s_waitcnt lgkmcnt(0)
	v_cndmask_b32_e64 v57, v8, -v8, s[8:9]
	ds_bpermute_b32 v7, v0, v46
	ds_bpermute_b32 v8, v0, v67
	v_pk_mul_f32 v[64:65], v[102:103], v[64:65]
	v_pk_mul_f32 v[56:57], v[102:103], v[56:57]
	v_pk_fma_f32 v[42:43], v[48:49], v[60:61], v[64:65]
	s_waitcnt lgkmcnt(1)
	v_cndmask_b32_e64 v64, v7, -v7, s[8:9]
	s_waitcnt lgkmcnt(0)
	v_cndmask_b32_e64 v44, v8, -v8, s[8:9]
	ds_bpermute_b32 v7, v0, v47
	ds_bpermute_b32 v8, v0, v45
	v_mov_b32_e32 v60, v67
	v_mov_b32_e32 v65, v47
	s_waitcnt lgkmcnt(1)
	v_cndmask_b32_e64 v69, v7, -v7, s[8:9]
	s_waitcnt lgkmcnt(0)
	v_cndmask_b32_e64 v61, v8, -v8, s[8:9]
	ds_bpermute_b32 v7, v0, v38
	ds_bpermute_b32 v8, v0, v62
	v_pk_mul_f32 v[66:67], v[98:99], v[68:69]
	v_pk_mul_f32 v[60:61], v[98:99], v[60:61]
	v_pk_fma_f32 v[46:47], v[50:51], v[64:65], v[66:67]
	s_waitcnt lgkmcnt(1)
	v_cndmask_b32_e64 v66, v7, -v7, s[8:9]
	s_waitcnt lgkmcnt(0)
	v_cndmask_b32_e64 v64, v8, -v8, s[8:9]
	ds_bpermute_b32 v7, v0, v39
	ds_bpermute_b32 v8, v0, v58
	v_mov_b32_e32 v98, v62
	v_mov_b32_e32 v68, v38
	v_mov_b32_e32 v67, v39
	s_waitcnt lgkmcnt(1)
	v_cndmask_b32_e64 v69, v7, -v7, s[8:9]
	s_waitcnt lgkmcnt(0)
	v_cndmask_b32_e64 v99, v8, -v8, s[8:9]
	v_mov_b32_e32 v7, v9
	v_pk_mul_f32 v[8:9], v[6:7], v[98:99]
	v_pk_mul_f32 v[6:7], v[6:7], v[68:69]
	v_mov_b32_e32 v65, v58
	v_pk_fma_f32 v[38:39], v[52:53], v[66:67], v[6:7]
	ds_bpermute_b32 v7, v0, v63
	ds_bpermute_b32 v6, v0, v40
	v_mov_b32_e32 v98, v3
	v_mov_b32_e32 v99, v5
	v_mov_b32_e32 v66, v59
	s_waitcnt lgkmcnt(1)
	v_cndmask_b32_e64 v58, v7, -v7, s[8:9]
	ds_bpermute_b32 v7, v0, v41
	ds_bpermute_b32 v0, v0, v59
	s_waitcnt lgkmcnt(2)
	v_cndmask_b32_e64 v6, v6, -v6, s[8:9]
	v_mov_b32_e32 v68, v2
	v_mov_b32_e32 v69, v4
	s_waitcnt lgkmcnt(1)
	v_cndmask_b32_e64 v7, v7, -v7, s[8:9]
	s_waitcnt lgkmcnt(0)
	v_cndmask_b32_e64 v67, v0, -v0, s[8:9]
	v_pk_mul_f32 v[6:7], v[98:99], v[6:7]
	v_pk_mul_f32 v[4:5], v[4:5], v[66:67]
	v_pk_fma_f32 v[40:41], v[68:69], v[40:41], v[6:7]
	v_mul_f32_e32 v2, v2, v63
	v_mul_f32_e32 v6, v3, v58
	v_mov_b32_e32 v3, v4
	v_mov_b32_e32 v7, v5
	v_pk_fma_f32 v[66:67], v[48:49], v[54:55], v[56:57]
	v_pk_fma_f32 v[4:5], v[50:51], v[44:45], v[60:61]
	v_pk_fma_f32 v[62:63], v[52:53], v[64:65], v[8:9]
	v_pk_add_f32 v[2:3], v[2:3], v[6:7]
	v_mov_b32_e32 v44, v67
	v_mov_b32_e32 v67, v4
	v_mov_b32_e32 v45, v5
	v_mov_b32_e32 v58, v63
	v_mov_b32_e32 v63, v2
	v_mov_b32_e32 v59, v3
; DI uint4 pack8(const float* f) { uint4 o; o.x = pk2(f[0], f[1]); o.y = pk2(f[2], f[3]); o.z = pk2(f[4], f[5]); o.w = pk2(f[6], f[7]); return o; }
; DI void phase_ret_prep(PrmC p, int ri, unsigned char* smem) {
;     ...
;               float q[8], k[8]; unpack8(*(const uint4*)(P0 + (size_t)row * 2048 + hp * 256 + c), q); unpack8(*(const uint4*)(P0 + (size_t)row * 2048 + 1024 + hp * 256 + c), k);
;     ...
; #pragma unroll
;               for (int e = 0; e < 8; ++e) k[e] *= 0.08838834764831845f;
;               const uint4 kq = pack8(k);
;               *(uint4*)(QR + (size_t)row * 1024 + hp * 256 + c) = pack8(q); *(uint4*)(KR + (size_t)row * 1024 + hp * 256 + c) = kq;
;               *(uint4*)(kt_l + pos * 264 + c) = kq;
.LBB0_680:
	v_and_b32_sdwa v3, v47, v242 dst_sel:DWORD dst_unused:UNUSED_PAD src0_sel:WORD_1 src1_sel:DWORD
	v_and_b32_sdwa v4, v43, v242 dst_sel:DWORD dst_unused:UNUSED_PAD src0_sel:WORD_1 src1_sel:DWORD
	v_and_b32_sdwa v0, v46, v242 dst_sel:DWORD dst_unused:UNUSED_PAD src0_sel:WORD_1 src1_sel:DWORD
	v_and_b32_sdwa v2, v42, v242 dst_sel:DWORD dst_unused:UNUSED_PAD src0_sel:WORD_1 src1_sel:DWORD
	v_add3_u32 v3, v47, v3, s71
	v_add3_u32 v4, v43, v4, s71
	v_lshlrev_b64 v[6:7], 11, v[36:37]
	v_add3_u32 v2, v42, v2, s71
	v_add3_u32 v0, v46, v0, s71
	v_and_b32_e32 v3, 0xffff0000, v3
	v_and_b32_e32 v4, 0xffff0000, v4
	v_and_b32_sdwa v5, v41, v242 dst_sel:DWORD dst_unused:UNUSED_PAD src0_sel:WORD_1 src1_sel:DWORD
	v_and_b32_sdwa v37, v39, v242 dst_sel:DWORD dst_unused:UNUSED_PAD src0_sel:WORD_1 src1_sel:DWORD
	v_or_b32_sdwa v3, v3, v0 dst_sel:DWORD dst_unused:UNUSED_PAD src0_sel:DWORD src1_sel:WORD_1
	v_or_b32_sdwa v2, v4, v2 dst_sel:DWORD dst_unused:UNUSED_PAD src0_sel:DWORD src1_sel:WORD_1
	v_and_b32_sdwa v0, v40, v242 dst_sel:DWORD dst_unused:UNUSED_PAD src0_sel:WORD_1 src1_sel:DWORD
	v_and_b32_sdwa v4, v38, v242 dst_sel:DWORD dst_unused:UNUSED_PAD src0_sel:WORD_1 src1_sel:DWORD
	v_add3_u32 v5, v41, v5, s71
	v_add3_u32 v37, v39, v37, s71
	v_add3_u32 v4, v38, v4, s71
	v_add3_u32 v0, v40, v0, s71
	v_and_b32_e32 v5, 0xffff0000, v5
	v_and_b32_e32 v37, 0xffff0000, v37
	v_lshl_add_u64 v[8:9], v[30:31], 0, v[6:7]
	v_or_b32_sdwa v5, v5, v0 dst_sel:DWORD dst_unused:UNUSED_PAD src0_sel:DWORD src1_sel:WORD_1
	v_or_b32_sdwa v4, v37, v4 dst_sel:DWORD dst_unused:UNUSED_PAD src0_sel:DWORD src1_sel:WORD_1
	global_store_dwordx4 v[8:9], v[2:5], off
	v_add_u32_e32 v38, 2, v36
	v_lshl_add_u64 v[6:7], v[32:33], 0, v[6:7]
	v_pk_mul_f32 v[2:3], v[66:67], s[62:63] op_sel_hi:[1,0]
	v_pk_mul_f32 v[4:5], v[44:45], s[62:63] op_sel_hi:[1,0]
	v_and_b32_sdwa v8, v2, v242 dst_sel:DWORD dst_unused:UNUSED_PAD src0_sel:WORD_1 src1_sel:DWORD
	v_and_b32_sdwa v0, v3, v242 dst_sel:DWORD dst_unused:UNUSED_PAD src0_sel:WORD_1 src1_sel:DWORD
	v_add3_u32 v2, v2, v8, s71
	v_and_b32_sdwa v8, v4, v242 dst_sel:DWORD dst_unused:UNUSED_PAD src0_sel:WORD_1 src1_sel:DWORD
	v_add3_u32 v0, v3, v0, s71
	v_and_b32_sdwa v3, v5, v242 dst_sel:DWORD dst_unused:UNUSED_PAD src0_sel:WORD_1 src1_sel:DWORD
	v_add3_u32 v4, v4, v8, s71
	v_add3_u32 v3, v5, v3, s71
	v_and_b32_e32 v4, 0xffff0000, v4
	v_and_b32_e32 v3, 0xffff0000, v3
	v_or_b32_sdwa v2, v4, v2 dst_sel:DWORD dst_unused:UNUSED_PAD src0_sel:DWORD src1_sel:WORD_1
	v_pk_mul_f32 v[4:5], v[62:63], s[62:63] op_sel_hi:[1,0]
	v_or_b32_sdwa v3, v3, v0 dst_sel:DWORD dst_unused:UNUSED_PAD src0_sel:DWORD src1_sel:WORD_1
	v_pk_mul_f32 v[8:9], v[58:59], s[62:63] op_sel_hi:[1,0]
	v_and_b32_sdwa v0, v5, v242 dst_sel:DWORD dst_unused:UNUSED_PAD src0_sel:WORD_1 src1_sel:DWORD
	v_and_b32_sdwa v37, v4, v242 dst_sel:DWORD dst_unused:UNUSED_PAD src0_sel:WORD_1 src1_sel:DWORD
	v_add3_u32 v4, v4, v37, s71
	v_add3_u32 v0, v5, v0, s71
	v_and_b32_sdwa v5, v9, v242 dst_sel:DWORD dst_unused:UNUSED_PAD src0_sel:WORD_1 src1_sel:DWORD
	v_and_b32_sdwa v37, v8, v242 dst_sel:DWORD dst_unused:UNUSED_PAD src0_sel:WORD_1 src1_sel:DWORD
	v_add3_u32 v5, v9, v5, s71
	v_add3_u32 v8, v8, v37, s71
	v_and_b32_e32 v5, 0xffff0000, v5
	v_and_b32_e32 v8, 0xffff0000, v8
	v_or_b32_sdwa v5, v5, v0 dst_sel:DWORD dst_unused:UNUSED_PAD src0_sel:DWORD src1_sel:WORD_1
	v_or_b32_sdwa v4, v8, v4 dst_sel:DWORD dst_unused:UNUSED_PAD src0_sel:DWORD src1_sel:WORD_1
	v_ashrrev_i32_e32 v39, 31, v38
	global_store_dwordx4 v[6:7], v[2:5], off
	v_lshlrev_b64 v[6:7], 12, v[38:39]
	v_lshl_add_u64 v[40:41], v[34:35], 0, v[6:7]
	v_mov_b64_e32 v[6:7], v[116:117]
	v_mov_b64_e32 v[8:9], v[118:119]
	v_mov_b64_e32 v[50:51], v[120:121]
	v_mov_b64_e32 v[52:53], v[122:123]
	s_and_b64 vcc, exec, s[10:11]
	ds_write_b128 v96, v[2:5]
	v_lshlrev_b32_e32 v44, 16, v6
	v_and_b32_e32 v45, 0xffff0000, v6
	v_lshlrev_b32_e32 v48, 16, v7
	v_and_b32_e32 v49, 0xffff0000, v7
	v_lshlrev_b32_e32 v40, 16, v8
	v_and_b32_e32 v41, 0xffff0000, v8
	v_lshlrev_b32_e32 v42, 16, v9
	v_and_b32_e32 v43, 0xffff0000, v9
	v_lshlrev_b32_e32 v68, 16, v50
	v_and_b32_e32 v46, 0xffff0000, v50
	v_lshlrev_b32_e32 v69, 16, v51
	v_and_b32_e32 v47, 0xffff0000, v51
	v_lshlrev_b32_e32 v64, 16, v52
	v_and_b32_e32 v60, 0xffff0000, v52
	v_lshlrev_b32_e32 v65, 16, v53
	v_and_b32_e32 v61, 0xffff0000, v53
	s_cbranch_vccnz .LBB0_677
; DI void phase_ret_prep(PrmC p, int ri, unsigned char* smem) {
;     ...
;               if (lat) {
;                   const float2* rt = RT + (size_t)(row & 2047) * 64 + (wo & 63);
; #pragma unroll
;                   for (int e = 0; e < 8; ++e) { const float2 cs = rt[e]; const float qp = __shfl_xor(q[e], 8), kp = __shfl_xor(k[e], 8);
;                       q[e] = q[e] * cs.x + (firsth ? -qp : qp) * cs.y; k[e] = k[e] * cs.x + (firsth ? -kp : kp) * cs.y; }
;               }
	v_add_u32_e32 v0, 0x80, v97
	v_and_b32_e32 v0, 0x1ffc0, v0
	v_lshlrev_b32_e32 v0, 3, v0
	v_and_b32_e32 v4, 64, v240
	v_lshl_add_u64 v[2:3], v[18:19], 0, v[0:1]
	v_xor_b32_e32 v0, 8, v240
	v_add_u32_e32 v4, 64, v4
	v_cmp_lt_i32_e32 vcc, v0, v4
	v_mov_b64_e32 v[6:7], v[140:141]
	v_mov_b64_e32 v[8:9], v[142:143]
	v_mov_b64_e32 v[98:99], v[144:145]
	v_mov_b64_e32 v[100:101], v[146:147]
	v_mov_b64_e32 v[102:103], v[148:149]
	v_mov_b64_e32 v[104:105], v[150:151]
	s_nop 0
	v_mov_b64_e32 v[2:3], v[152:153]
	v_mov_b64_e32 v[4:5], v[154:155]
	v_cndmask_b32_e32 v0, v240, v0, vcc
	v_lshlrev_b32_e32 v0, 2, v0
	v_mov_b32_e32 v66, v44
	v_mov_b32_e32 v63, v45
	v_mov_b32_e32 v57, v46
	v_mov_b32_e32 v58, v68
	v_mov_b32_e32 v54, v7
	v_mov_b32_e32 v55, v8
	ds_bpermute_b32 v7, v0, v44
	ds_bpermute_b32 v8, v0, v68
	v_mov_b32_e32 v50, v103
	v_mov_b32_e32 v103, v105
	v_mov_b32_e32 v51, v104
	s_waitcnt lgkmcnt(1)
	v_cndmask_b32_e64 v62, v7, -v7, s[8:9]
	s_waitcnt lgkmcnt(0)
	v_cndmask_b32_e64 v56, v8, -v8, s[8:9]
	ds_bpermute_b32 v7, v0, v45
	ds_bpermute_b32 v8, v0, v46
	v_mov_b32_e32 v52, v99
	v_mov_b32_e32 v99, v101
	v_mov_b32_e32 v53, v100
	s_waitcnt lgkmcnt(1)
	v_cndmask_b32_e64 v67, v7, -v7, s[8:9]
	s_waitcnt lgkmcnt(0)
	v_cndmask_b32_e64 v59, v8, -v8, s[8:9]
	ds_bpermute_b32 v7, v0, v48
	ds_bpermute_b32 v8, v0, v69
	v_pk_mul_f32 v[66:67], v[102:103], v[66:67]
	v_pk_mul_f32 v[58:59], v[102:103], v[58:59]
	v_pk_fma_f32 v[44:45], v[50:51], v[62:63], v[66:67]
	s_waitcnt lgkmcnt(1)
	v_cndmask_b32_e64 v66, v7, -v7, s[8:9]
	s_waitcnt lgkmcnt(0)
	v_cndmask_b32_e64 v46, v8, -v8, s[8:9]
	ds_bpermute_b32 v7, v0, v49
	ds_bpermute_b32 v8, v0, v47
	v_mov_b32_e32 v102, v48
	v_mov_b32_e32 v62, v69
	v_mov_b32_e32 v67, v49
	s_waitcnt lgkmcnt(1)
	v_cndmask_b32_e64 v103, v7, -v7, s[8:9]
	s_waitcnt lgkmcnt(0)
	v_cndmask_b32_e64 v63, v8, -v8, s[8:9]
	ds_bpermute_b32 v7, v0, v40
	ds_bpermute_b32 v8, v0, v64
	v_pk_mul_f32 v[68:69], v[98:99], v[102:103]
	v_pk_mul_f32 v[62:63], v[98:99], v[62:63]
	v_pk_fma_f32 v[48:49], v[52:53], v[66:67], v[68:69]
	s_waitcnt lgkmcnt(1)
	v_cndmask_b32_e64 v68, v7, -v7, s[8:9]
	s_waitcnt lgkmcnt(0)
	v_cndmask_b32_e64 v66, v8, -v8, s[8:9]
	ds_bpermute_b32 v7, v0, v41
	ds_bpermute_b32 v8, v0, v60
	v_mov_b32_e32 v100, v64
	v_mov_b32_e32 v98, v40
	v_mov_b32_e32 v69, v41
	s_waitcnt lgkmcnt(1)
	v_cndmask_b32_e64 v99, v7, -v7, s[8:9]
	s_waitcnt lgkmcnt(0)
	v_cndmask_b32_e64 v101, v8, -v8, s[8:9]
	v_mov_b32_e32 v7, v9
	v_pk_mul_f32 v[8:9], v[6:7], v[100:101]
	v_pk_mul_f32 v[6:7], v[6:7], v[98:99]
	v_mov_b32_e32 v100, v3
	v_pk_fma_f32 v[40:41], v[54:55], v[68:69], v[6:7]
	ds_bpermute_b32 v7, v0, v65
	ds_bpermute_b32 v6, v0, v42
	v_mov_b32_e32 v101, v5
	v_mov_b32_e32 v68, v61
	v_mov_b32_e32 v98, v2
	s_waitcnt lgkmcnt(1)
	v_cndmask_b32_e64 v37, v7, -v7, s[8:9]
	ds_bpermute_b32 v7, v0, v43
	ds_bpermute_b32 v0, v0, v61
	s_waitcnt lgkmcnt(2)
	v_cndmask_b32_e64 v6, v6, -v6, s[8:9]
	v_mov_b32_e32 v99, v4
	v_mov_b32_e32 v67, v60
	s_waitcnt lgkmcnt(1)
	v_cndmask_b32_e64 v7, v7, -v7, s[8:9]
	s_waitcnt lgkmcnt(0)
	v_cndmask_b32_e64 v69, v0, -v0, s[8:9]
	v_pk_mul_f32 v[6:7], v[100:101], v[6:7]
	v_pk_mul_f32 v[4:5], v[4:5], v[68:69]
	v_pk_fma_f32 v[42:43], v[98:99], v[42:43], v[6:7]
	v_mul_f32_e32 v2, v2, v65
	v_mul_f32_e32 v6, v3, v37
	v_mov_b32_e32 v3, v4
	v_mov_b32_e32 v7, v5
	v_pk_fma_f32 v[68:69], v[50:51], v[56:57], v[58:59]
	v_pk_fma_f32 v[4:5], v[52:53], v[46:47], v[62:63]
	v_pk_fma_f32 v[64:65], v[54:55], v[66:67], v[8:9]
	v_pk_add_f32 v[2:3], v[2:3], v[6:7]
	v_mov_b32_e32 v46, v69
	v_mov_b32_e32 v69, v4
	v_mov_b32_e32 v47, v5
	v_mov_b32_e32 v60, v65
	v_mov_b32_e32 v65, v2
	v_mov_b32_e32 v61, v3
	s_branch .LBB0_677
